# grid barrier leader: XCD release atomic issued before its own L1 invalidate (on top of version 51)
# baseline (speedup 1.0000x reference)
.LBB0_130:
	s_or_b64 exec, exec, s[4:5]
	s_mov_b64 s[4:5], exec
	v_mbcnt_lo_u32_b32 v1, s4, 0
	v_mbcnt_hi_u32_b32 v1, s5, v1
	v_cmp_eq_u32_e32 vcc, 0, v1
	s_waitcnt vmcnt(0)
	s_and_saveexec_b64 s[8:9], vcc
	s_cbranch_execz .LBB0_132
	s_bcnt1_i32_b64 s4, s[4:5]
	v_mov_b32_e32 v1, 0
	v_mov_b32_e32 v2, s4
	global_atomic_add v1, v2, s[6:7]
.LBB0_132:
	s_or_b64 exec, exec, s[8:9]
	buffer_inv sc1
	s_waitcnt vmcnt(0)

.LBB0_667:
	s_or_b64 exec, exec, s[2:3]
	s_mov_b64 s[2:3], exec
	v_mbcnt_lo_u32_b32 v1, s2, 0
	v_mbcnt_hi_u32_b32 v1, s3, v1
	v_cmp_eq_u32_e32 vcc, 0, v1
	s_waitcnt vmcnt(0)
	s_and_saveexec_b64 s[6:7], vcc
	s_cbranch_execz .LBB0_669
	s_bcnt1_i32_b64 s2, s[2:3]
	v_mov_b32_e32 v1, 0
	v_mov_b32_e32 v2, s2
	global_atomic_add v1, v2, s[4:5]
.LBB0_669:
	s_or_b64 exec, exec, s[6:7]
	buffer_inv sc1
	s_waitcnt vmcnt(0)
